# proj q/k-norm epilogue: the two gain-load round trips merged (4 loads issued together, counted vmcnt(2)/vmcnt(0)); on v91
# baseline (speedup 1.0000x reference)
; #define PG8_GAS __attribute__((address_space(1)))
; __device__ __forceinline__ unsigned cvtpk(float lo, float hi) { f32x2 v = {lo, hi}; bf16x2_t b = __builtin_convertvector(v, bf16x2_t); return __builtin_bit_cast(unsigned, b); }
;     __device__ __forceinline__ void operator()(const f32x4 (&acc)[2][2][4][2], const Unit& u, int wr, int wc, int fr, int fq) const {
;     ...
;         if (u.pn < 4) {
;             const float* g = (u.pn < 2) ? gq : gk; const float sc = (u.pn < 2) ? 0.125f * 1.4426950408889634f : 1.0f;
;             f32x4 gv[2][2];
; #pragma unroll
;             for (int bj = 0; bj < 2; ++bj)
; #pragma unroll
;                 for (int n = 0; n < 2; ++n) gv[bj][n] = *(const PG8_GAS f32x4*)(g + 32 * bj + 8 * fq + 4 * n) * sc;
; #pragma unroll
;             for (int ai = 0; ai < 2; ++ai)
; #pragma unroll
;                 for (int m = 0; m < 4; ++m) {
;                     float ss = 0.f;
; #pragma unroll
;                     for (int bj = 0; bj < 2; ++bj)
; #pragma unroll
;                         for (int n = 0; n < 2; ++n) { const f32x4 x = acc[ai][bj][m][n]; ss += (x[0] * x[0] + x[1] * x[1]) + (x[2] * x[2] + x[3] * x[3]); }
;                     ss += __shfl_xor(ss, 16); ss += __shfl_xor(ss, 32);
;                     const float rstd = 1.0f / sqrtf(ss * (1.0f / 64.0f) + 1e-6f);
;                     bf16_t* p = O + (size_t)(row0 + ai * HALF + m * 16) * 3072 + colh;
; #pragma unroll
;                     for (int bj = 0; bj < 2; ++bj) {
;                         const f32x4 v0 = acc[ai][bj][m][0] * rstd * gv[bj][0], v1 = acc[ai][bj][m][1] * rstd * gv[bj][1];
;                         u32x4 w; w.x = cvtpk(v0[0], v0[1]); w.y = cvtpk(v0[2], v0[3]); w.z = cvtpk(v1[0], v1[1]); w.w = cvtpk(v1[2], v1[3]);
;                         __builtin_nontemporal_store(w, (PG8_GAS u32x4*)(p + 32 * bj));
.LBB0_259:
	s_andn2_b64 vcc, exec, s[6:7]
	s_cbranch_vccnz .LBB0_261
	s_cmp_lt_i32 s14, 2
	s_cselect_b64 vcc, -1, 0
	s_and_b64 s[6:7], vcc, exec
	s_cselect_b32 s7, s11, s65
	s_cselect_b32 s6, s10, s64
	global_load_dwordx4 v[152:155], v167, s[6:7] offset:16
	global_load_dwordx4 v[144:147], v167, s[6:7]
	global_load_dwordx4 v[184:187], v167, s[6:7] offset:144
	global_load_dwordx4 v[188:191], v167, s[6:7] offset:128
	v_cndmask_b32_e32 v170, 1.0, v225, vcc
	v_cmp_lt_i32_e32 vcc, v218, v213
	v_pk_mul_f32 v[178:179], v[130:131], v[130:131]
	s_waitcnt vmcnt(2)
	v_pk_mul_f32 v[148:149], v[170:171], v[146:147] op_sel_hi:[0,1]
	v_pk_mul_f32 v[150:151], v[170:171], v[144:145] op_sel_hi:[0,1]
	v_pk_mul_f32 v[144:145], v[170:171], v[154:155] op_sel_hi:[0,1]
	v_pk_mul_f32 v[146:147], v[170:171], v[152:153] op_sel_hi:[0,1]
	s_waitcnt vmcnt(0)
	v_pk_mul_f32 v[156:157], v[170:171], v[190:191] op_sel_hi:[0,1]
	v_pk_mul_f32 v[154:155], v[170:171], v[184:185] op_sel_hi:[0,1]
	v_cndmask_b32_e32 v160, v212, v218, vcc
	v_cmp_lt_i32_e32 vcc, v219, v213
	v_pk_mul_f32 v[158:159], v[170:171], v[188:189] op_sel_hi:[0,1]
	v_pk_mul_f32 v[152:153], v[170:171], v[186:187] op_sel_hi:[0,1]
	v_lshlrev_b32_e32 v171, 2, v160
	v_cndmask_b32_e32 v160, v212, v219, vcc
	v_lshlrev_b32_e32 v170, 2, v160
	v_pk_mul_f32 v[160:161], v[132:133], v[132:133]
	v_ashrrev_i32_e32 v163, 31, v0
	v_pk_mov_b32 v[180:181], v[178:179], v[160:161] op_sel:[1,0]
	v_mov_b32_e32 v179, v161
	v_pk_add_f32 v[160:161], v[180:181], v[178:179]
	v_pk_mul_f32 v[178:179], v[128:129], v[128:129]
	v_pk_mul_f32 v[180:181], v[126:127], v[126:127]
	v_mov_b32_e32 v162, v0
	v_pk_mov_b32 v[182:183], v[180:181], v[178:179] op_sel:[1,0]
	v_mov_b32_e32 v181, v179
	v_pk_add_f32 v[178:179], v[182:183], v[180:181]
	v_mul_f32_e32 v0, v118, v118
	v_mul_f32_e32 v180, v119, v119
	v_pk_add_f32 v[160:161], v[160:161], v[160:161] op_sel:[0,1] op_sel_hi:[1,0]
	v_pk_add_f32 v[178:179], v[178:179], v[178:179] op_sel:[0,1] op_sel_hi:[1,0]
	v_mov_b32_e32 v161, v0
	v_mov_b32_e32 v179, v180
	v_mul_f32_e32 v0, v123, v123
	v_mul_f32_e32 v181, v120, v120
	v_pk_add_f32 v[160:161], v[160:161], v[178:179]
	v_pk_fma_f32 v[178:179], v[122:123], v[122:123], v[0:1] op_sel_hi:[1,1,0]
	v_mul_f32_e32 v0, v125, v125
	v_mul_f32_e32 v182, v121, v121
	v_mov_b32_e32 v179, v181
	v_pk_fma_f32 v[180:181], v[124:125], v[124:125], v[0:1] op_sel_hi:[1,1,0]
	v_lshlrev_b64 v[162:163], 1, v[162:163]
	v_mov_b32_e32 v181, v182
	v_pk_add_f32 v[178:179], v[178:179], v[180:181]
	s_nop 0
	v_pk_add_f32 v[160:161], v[160:161], v[178:179]
	s_nop 0
	v_add_f32_e32 v0, v160, v161
	ds_bpermute_b32 v160, v171, v0
	s_waitcnt lgkmcnt(0)
	v_add_f32_e32 v0, v0, v160
	ds_bpermute_b32 v160, v170, v0
	s_waitcnt lgkmcnt(0)
	v_add_f32_e32 v0, v0, v160
	v_fmamk_f32 v0, v0, 0x3c800000, v220
	v_cmp_gt_f32_e32 vcc, s45, v0
	v_mul_f32_e32 v160, 0x4f800000, v0
	s_nop 0
	v_cndmask_b32_e32 v0, v0, v160, vcc
	v_sqrt_f32_e32 v160, v0
	s_nop 0
	v_add_u32_e32 v161, -1, v160
	v_fma_f32 v178, -v161, v160, v0
	v_cmp_ge_f32_e64 s[6:7], 0, v178
	v_add_u32_e32 v178, 1, v160
	s_nop 0
	v_cndmask_b32_e64 v161, v160, v161, s[6:7]
	v_fma_f32 v160, -v178, v160, v0
	v_cmp_lt_f32_e64 s[6:7], 0, v160
	s_nop 1
	v_cndmask_b32_e64 v160, v161, v178, s[6:7]
	v_mul_f32_e32 v161, 0x37800000, v160
	v_cndmask_b32_e32 v160, v160, v161, vcc
	v_cmp_class_f32_e32 vcc, v0, v221
	s_nop 1
	v_cndmask_b32_e32 v0, v160, v0, vcc
	v_div_scale_f32 v160, s[6:7], v0, v0, 1.0
	v_rcp_f32_e32 v161, v160
	s_nop 0
	v_fma_f32 v178, -v160, v161, 1.0
	v_fmac_f32_e32 v161, v178, v161
	v_div_scale_f32 v178, vcc, 1.0, v0, 1.0
	v_mul_f32_e32 v179, v178, v161
	v_fma_f32 v180, -v160, v179, v178
	v_fmac_f32_e32 v179, v180, v161
	v_fma_f32 v160, -v160, v179, v178
	v_div_fmas_f32 v160, v160, v161, v179
	v_div_fixup_f32 v0, v160, v0, 1.0
	v_mov_b64_e32 v[160:161], s[8:9]
	v_pk_mul_f32 v[130:131], v[130:131], v[0:1] op_sel_hi:[1,0]
	v_pk_mul_f32 v[132:133], v[132:133], v[0:1] op_sel_hi:[1,0]
	v_pk_mul_f32 v[126:127], v[126:127], v[0:1] op_sel_hi:[1,0]
	v_pk_mul_f32 v[128:129], v[128:129], v[0:1] op_sel_hi:[1,0]
	v_mad_i64_i32 v[178:179], s[6:7], v177, s44, v[160:161]
	v_pk_mul_f32 v[132:133], v[148:149], v[132:133]
	v_pk_mul_f32 v[130:131], v[150:151], v[130:131]
	v_pk_mul_f32 v[180:181], v[144:145], v[128:129]
	v_pk_mul_f32 v[128:129], v[146:147], v[126:127]
	v_lshl_add_u64 v[178:179], v[178:179], 0, v[162:163]
	v_cvt_pk_bf16_f32 v126, v130, v131
	v_cvt_pk_bf16_f32 v127, v132, v133
	v_cvt_pk_bf16_f32 v128, v128, v129
	v_cvt_pk_bf16_f32 v129, v180, v181
	v_pk_mul_f32 v[122:123], v[122:123], v[0:1] op_sel_hi:[1,0]
	v_pk_mul_f32 v[124:125], v[124:125], v[0:1] op_sel_hi:[1,0]
	v_pk_mul_f32 v[118:119], v[118:119], v[0:1] op_sel_hi:[1,0]
	v_pk_mul_f32 v[120:121], v[120:121], v[0:1] op_sel_hi:[1,0]
	global_store_dwordx4 v[178:179], v[126:129], off nt
	v_pk_mul_f32 v[124:125], v[156:157], v[124:125]
	v_pk_mul_f32 v[122:123], v[158:159], v[122:123]
	v_pk_mul_f32 v[126:127], v[152:153], v[120:121]
	v_pk_mul_f32 v[120:121], v[154:155], v[118:119]
	v_cvt_pk_bf16_f32 v118, v122, v123
	v_cvt_pk_bf16_f32 v119, v124, v125
	v_cvt_pk_bf16_f32 v120, v120, v121
	v_cvt_pk_bf16_f32 v121, v126, v127
	global_store_dwordx4 v[178:179], v[118:121], off offset:64 nt
	v_mul_f32_e32 v0, v102, v102
	s_nop 0
	v_pk_mul_f32 v[118:119], v[116:117], v[116:117]
	v_pk_mul_f32 v[120:121], v[114:115], v[114:115]
	s_nop 0
	v_pk_mov_b32 v[122:123], v[120:121], v[118:119] op_sel:[1,0]
	v_mov_b32_e32 v121, v119
	v_pk_add_f32 v[118:119], v[122:123], v[120:121]
	v_pk_mul_f32 v[120:121], v[112:113], v[112:113]
	v_pk_mul_f32 v[122:123], v[110:111], v[110:111]
	v_pk_add_f32 v[118:119], v[118:119], v[118:119] op_sel:[0,1] op_sel_hi:[1,0]
	v_pk_mov_b32 v[124:125], v[122:123], v[120:121] op_sel:[1,0]
	v_mov_b32_e32 v123, v121
	v_pk_add_f32 v[120:121], v[124:125], v[122:123]
	v_mul_f32_e32 v122, v103, v103
	v_pk_add_f32 v[120:121], v[120:121], v[120:121] op_sel:[0,1] op_sel_hi:[1,0]
	v_mov_b32_e32 v119, v0
	v_mov_b32_e32 v121, v122
	v_mul_f32_e32 v0, v107, v107
	v_mul_f32_e32 v123, v104, v104
	v_pk_add_f32 v[118:119], v[118:119], v[120:121]
	v_pk_fma_f32 v[120:121], v[106:107], v[106:107], v[0:1] op_sel_hi:[1,1,0]
	v_mul_f32_e32 v0, v109, v109
	v_mul_f32_e32 v124, v105, v105
	v_mov_b32_e32 v121, v123
	v_pk_fma_f32 v[122:123], v[108:109], v[108:109], v[0:1] op_sel_hi:[1,1,0]
	s_nop 0
	v_mov_b32_e32 v123, v124
	v_pk_add_f32 v[120:121], v[120:121], v[122:123]
	s_nop 0
	v_pk_add_f32 v[118:119], v[118:119], v[120:121]
	s_nop 0
	v_add_f32_e32 v0, v118, v119
	ds_bpermute_b32 v118, v171, v0
	s_waitcnt lgkmcnt(0)
; #define PG8_GAS __attribute__((address_space(1)))
; __device__ __forceinline__ unsigned cvtpk(float lo, float hi) { f32x2 v = {lo, hi}; bf16x2_t b = __builtin_convertvector(v, bf16x2_t); return __builtin_bit_cast(unsigned, b); }
;     __device__ __forceinline__ void operator()(const f32x4 (&acc)[2][2][4][2], const Unit& u, int wr, int wc, int fr, int fq) const {
;     ...
;                     float ss = 0.f;
; #pragma unroll
;                     for (int bj = 0; bj < 2; ++bj)
; #pragma unroll
;                         for (int n = 0; n < 2; ++n) { const f32x4 x = acc[ai][bj][m][n]; ss += (x[0] * x[0] + x[1] * x[1]) + (x[2] * x[2] + x[3] * x[3]); }
;                     ss += __shfl_xor(ss, 16); ss += __shfl_xor(ss, 32);
;                     const float rstd = 1.0f / sqrtf(ss * (1.0f / 64.0f) + 1e-6f);
;                     bf16_t* p = O + (size_t)(row0 + ai * HALF + m * 16) * 3072 + colh;
; #pragma unroll
;                     for (int bj = 0; bj < 2; ++bj) {
;                         const f32x4 v0 = acc[ai][bj][m][0] * rstd * gv[bj][0], v1 = acc[ai][bj][m][1] * rstd * gv[bj][1];
;                         u32x4 w; w.x = cvtpk(v0[0], v0[1]); w.y = cvtpk(v0[2], v0[3]); w.z = cvtpk(v1[0], v1[1]); w.w = cvtpk(v1[2], v1[3]);
;                         __builtin_nontemporal_store(w, (PG8_GAS u32x4*)(p + 32 * bj));
;                     }
	v_add_f32_e32 v0, v0, v118
	ds_bpermute_b32 v118, v170, v0
	s_waitcnt lgkmcnt(0)
	v_add_f32_e32 v0, v0, v118
	v_fmamk_f32 v0, v0, 0x3c800000, v220
	v_cmp_gt_f32_e32 vcc, s45, v0
	v_mul_f32_e32 v118, 0x4f800000, v0
	s_nop 0
	v_cndmask_b32_e32 v0, v0, v118, vcc
	v_sqrt_f32_e32 v118, v0
	s_nop 0
	v_add_u32_e32 v119, -1, v118
	v_fma_f32 v120, -v119, v118, v0
	v_cmp_ge_f32_e64 s[6:7], 0, v120
	v_add_u32_e32 v120, 1, v118
	s_nop 0
	v_cndmask_b32_e64 v119, v118, v119, s[6:7]
	v_fma_f32 v118, -v120, v118, v0
	v_cmp_lt_f32_e64 s[6:7], 0, v118
	s_nop 1
	v_cndmask_b32_e64 v118, v119, v120, s[6:7]
	v_mul_f32_e32 v119, 0x37800000, v118
	v_cndmask_b32_e32 v118, v118, v119, vcc
	v_cmp_class_f32_e32 vcc, v0, v221
	s_nop 1
	v_cndmask_b32_e32 v0, v118, v0, vcc
	v_div_scale_f32 v118, s[6:7], v0, v0, 1.0
	v_rcp_f32_e32 v119, v118
	s_nop 0
	v_fma_f32 v120, -v118, v119, 1.0
	v_fmac_f32_e32 v119, v120, v119
	v_div_scale_f32 v120, vcc, 1.0, v0, 1.0
	v_mul_f32_e32 v121, v120, v119
	v_fma_f32 v122, -v118, v121, v120
	v_fmac_f32_e32 v121, v122, v119
	v_fma_f32 v118, -v118, v121, v120
	v_div_fmas_f32 v118, v118, v119, v121
	v_div_fixup_f32 v0, v118, v0, 1.0
	v_pk_mul_f32 v[114:115], v[114:115], v[0:1] op_sel_hi:[1,0]
	v_pk_mul_f32 v[116:117], v[116:117], v[0:1] op_sel_hi:[1,0]
	v_pk_mul_f32 v[110:111], v[110:111], v[0:1] op_sel_hi:[1,0]
	v_pk_mul_f32 v[112:113], v[112:113], v[0:1] op_sel_hi:[1,0]
	v_mad_i64_i32 v[118:119], s[6:7], v176, s44, v[160:161]
	v_pk_mul_f32 v[116:117], v[148:149], v[116:117]
	v_pk_mul_f32 v[114:115], v[150:151], v[114:115]
	v_pk_mul_f32 v[120:121], v[144:145], v[112:113]
	v_pk_mul_f32 v[112:113], v[146:147], v[110:111]
	v_lshl_add_u64 v[118:119], v[118:119], 0, v[162:163]
	v_cvt_pk_bf16_f32 v110, v114, v115
	v_cvt_pk_bf16_f32 v111, v116, v117
	v_cvt_pk_bf16_f32 v112, v112, v113
	v_cvt_pk_bf16_f32 v113, v120, v121
	v_pk_mul_f32 v[106:107], v[106:107], v[0:1] op_sel_hi:[1,0]
	v_pk_mul_f32 v[108:109], v[108:109], v[0:1] op_sel_hi:[1,0]
	v_pk_mul_f32 v[102:103], v[102:103], v[0:1] op_sel_hi:[1,0]
	v_pk_mul_f32 v[104:105], v[104:105], v[0:1] op_sel_hi:[1,0]
	global_store_dwordx4 v[118:119], v[110:113], off nt
	v_pk_mul_f32 v[108:109], v[156:157], v[108:109]
	v_pk_mul_f32 v[106:107], v[158:159], v[106:107]
	v_pk_mul_f32 v[110:111], v[152:153], v[104:105]
	v_pk_mul_f32 v[104:105], v[154:155], v[102:103]
	v_cvt_pk_bf16_f32 v102, v106, v107
	v_cvt_pk_bf16_f32 v103, v108, v109
	v_cvt_pk_bf16_f32 v104, v104, v105
	v_cvt_pk_bf16_f32 v105, v110, v111
	global_store_dwordx4 v[118:119], v[102:105], off offset:64 nt
	v_mul_f32_e32 v0, v86, v86
	s_nop 0
	v_pk_mul_f32 v[102:103], v[100:101], v[100:101]
	v_pk_mul_f32 v[104:105], v[98:99], v[98:99]
	s_nop 0
	v_pk_mov_b32 v[106:107], v[104:105], v[102:103] op_sel:[1,0]
	v_mov_b32_e32 v105, v103
	v_pk_add_f32 v[102:103], v[106:107], v[104:105]
	v_pk_mul_f32 v[104:105], v[96:97], v[96:97]
	v_pk_mul_f32 v[106:107], v[94:95], v[94:95]
	v_pk_add_f32 v[102:103], v[102:103], v[102:103] op_sel:[0,1] op_sel_hi:[1,0]
	v_pk_mov_b32 v[108:109], v[106:107], v[104:105] op_sel:[1,0]
	v_mov_b32_e32 v107, v105
	v_pk_add_f32 v[104:105], v[108:109], v[106:107]
	v_mul_f32_e32 v106, v87, v87
	v_pk_add_f32 v[104:105], v[104:105], v[104:105] op_sel:[0,1] op_sel_hi:[1,0]
	v_mov_b32_e32 v103, v0
	v_mov_b32_e32 v105, v106
	v_mul_f32_e32 v0, v91, v91
	v_mul_f32_e32 v107, v88, v88
	v_pk_add_f32 v[102:103], v[102:103], v[104:105]
	v_pk_fma_f32 v[104:105], v[90:91], v[90:91], v[0:1] op_sel_hi:[1,1,0]
	v_mul_f32_e32 v0, v93, v93
	v_mul_f32_e32 v108, v89, v89
	v_mov_b32_e32 v105, v107
	v_pk_fma_f32 v[106:107], v[92:93], v[92:93], v[0:1] op_sel_hi:[1,1,0]
	s_nop 0
	v_mov_b32_e32 v107, v108
	v_pk_add_f32 v[104:105], v[104:105], v[106:107]
	s_nop 0
	v_pk_add_f32 v[102:103], v[102:103], v[104:105]
	s_nop 0
	v_add_f32_e32 v0, v102, v103
	ds_bpermute_b32 v102, v171, v0
	s_waitcnt lgkmcnt(0)
	v_add_f32_e32 v0, v0, v102
	ds_bpermute_b32 v102, v170, v0
	s_waitcnt lgkmcnt(0)
	v_add_f32_e32 v0, v0, v102
	v_fmamk_f32 v0, v0, 0x3c800000, v220
	v_cmp_gt_f32_e32 vcc, s45, v0
	v_mul_f32_e32 v102, 0x4f800000, v0
	s_nop 0
	v_cndmask_b32_e32 v0, v0, v102, vcc
	v_sqrt_f32_e32 v102, v0
	s_nop 0
	v_add_u32_e32 v103, -1, v102
	v_fma_f32 v104, -v103, v102, v0
	v_cmp_ge_f32_e64 s[6:7], 0, v104
	v_add_u32_e32 v104, 1, v102
	s_nop 0
	v_cndmask_b32_e64 v103, v102, v103, s[6:7]
	v_fma_f32 v102, -v104, v102, v0
	v_cmp_lt_f32_e64 s[6:7], 0, v102
	s_nop 1
	v_cndmask_b32_e64 v102, v103, v104, s[6:7]
	v_mul_f32_e32 v103, 0x37800000, v102
	v_cndmask_b32_e32 v102, v102, v103, vcc
	v_cmp_class_f32_e32 vcc, v0, v221
	s_nop 1
	v_cndmask_b32_e32 v0, v102, v0, vcc
	v_div_scale_f32 v102, s[6:7], v0, v0, 1.0
	v_rcp_f32_e32 v103, v102
	s_nop 0
	v_fma_f32 v104, -v102, v103, 1.0
	v_fmac_f32_e32 v103, v104, v103
	v_div_scale_f32 v104, vcc, 1.0, v0, 1.0
	v_mul_f32_e32 v105, v104, v103
	v_fma_f32 v106, -v102, v105, v104
	v_fmac_f32_e32 v105, v106, v103
	v_fma_f32 v102, -v102, v105, v104
	v_div_fmas_f32 v102, v102, v103, v105
	v_div_fixup_f32 v0, v102, v0, 1.0
	v_pk_mul_f32 v[98:99], v[98:99], v[0:1] op_sel_hi:[1,0]
	v_pk_mul_f32 v[100:101], v[100:101], v[0:1] op_sel_hi:[1,0]
	v_pk_mul_f32 v[94:95], v[94:95], v[0:1] op_sel_hi:[1,0]
	v_pk_mul_f32 v[96:97], v[96:97], v[0:1] op_sel_hi:[1,0]
	v_mad_i64_i32 v[102:103], s[6:7], v175, s44, v[160:161]
	v_pk_mul_f32 v[100:101], v[148:149], v[100:101]
	v_pk_mul_f32 v[98:99], v[150:151], v[98:99]
	v_pk_mul_f32 v[104:105], v[144:145], v[96:97]
	v_pk_mul_f32 v[96:97], v[146:147], v[94:95]
	v_lshl_add_u64 v[102:103], v[102:103], 0, v[162:163]
	v_cvt_pk_bf16_f32 v94, v98, v99
	v_cvt_pk_bf16_f32 v95, v100, v101
	v_cvt_pk_bf16_f32 v96, v96, v97
; #define PG8_GAS __attribute__((address_space(1)))
; __device__ __forceinline__ unsigned cvtpk(float lo, float hi) { f32x2 v = {lo, hi}; bf16x2_t b = __builtin_convertvector(v, bf16x2_t); return __builtin_bit_cast(unsigned, b); }
;     __device__ __forceinline__ void operator()(const f32x4 (&acc)[2][2][4][2], const Unit& u, int wr, int wc, int fr, int fq) const {
;     ...
;                     float ss = 0.f;
; #pragma unroll
;                     for (int bj = 0; bj < 2; ++bj)
; #pragma unroll
;                         for (int n = 0; n < 2; ++n) { const f32x4 x = acc[ai][bj][m][n]; ss += (x[0] * x[0] + x[1] * x[1]) + (x[2] * x[2] + x[3] * x[3]); }
;                     ss += __shfl_xor(ss, 16); ss += __shfl_xor(ss, 32);
;                     const float rstd = 1.0f / sqrtf(ss * (1.0f / 64.0f) + 1e-6f);
;                     bf16_t* p = O + (size_t)(row0 + ai * HALF + m * 16) * 3072 + colh;
; #pragma unroll
;                     for (int bj = 0; bj < 2; ++bj) {
;                         const f32x4 v0 = acc[ai][bj][m][0] * rstd * gv[bj][0], v1 = acc[ai][bj][m][1] * rstd * gv[bj][1];
;                         u32x4 w; w.x = cvtpk(v0[0], v0[1]); w.y = cvtpk(v0[2], v0[3]); w.z = cvtpk(v1[0], v1[1]); w.w = cvtpk(v1[2], v1[3]);
;                         __builtin_nontemporal_store(w, (PG8_GAS u32x4*)(p + 32 * bj));
;                     }
	v_cvt_pk_bf16_f32 v97, v104, v105
	v_pk_mul_f32 v[90:91], v[90:91], v[0:1] op_sel_hi:[1,0]
	v_pk_mul_f32 v[92:93], v[92:93], v[0:1] op_sel_hi:[1,0]
	v_pk_mul_f32 v[86:87], v[86:87], v[0:1] op_sel_hi:[1,0]
	v_pk_mul_f32 v[88:89], v[88:89], v[0:1] op_sel_hi:[1,0]
	global_store_dwordx4 v[102:103], v[94:97], off nt
	v_pk_mul_f32 v[92:93], v[156:157], v[92:93]
	v_pk_mul_f32 v[90:91], v[158:159], v[90:91]
	v_pk_mul_f32 v[94:95], v[152:153], v[88:89]
	v_pk_mul_f32 v[88:89], v[154:155], v[86:87]
	v_cvt_pk_bf16_f32 v86, v90, v91
	v_cvt_pk_bf16_f32 v87, v92, v93
	v_cvt_pk_bf16_f32 v88, v88, v89
	v_cvt_pk_bf16_f32 v89, v94, v95
	global_store_dwordx4 v[102:103], v[86:89], off offset:64 nt
	v_mul_f32_e32 v0, v70, v70
	s_nop 0
	v_pk_mul_f32 v[86:87], v[84:85], v[84:85]
	v_pk_mul_f32 v[88:89], v[82:83], v[82:83]
	s_nop 0
	v_pk_mov_b32 v[90:91], v[88:89], v[86:87] op_sel:[1,0]
	v_mov_b32_e32 v89, v87
	v_pk_add_f32 v[86:87], v[90:91], v[88:89]
	v_pk_mul_f32 v[88:89], v[80:81], v[80:81]
	v_pk_mul_f32 v[90:91], v[78:79], v[78:79]
	v_pk_add_f32 v[86:87], v[86:87], v[86:87] op_sel:[0,1] op_sel_hi:[1,0]
	v_pk_mov_b32 v[92:93], v[90:91], v[88:89] op_sel:[1,0]
	v_mov_b32_e32 v91, v89
	v_pk_add_f32 v[88:89], v[92:93], v[90:91]
	v_mul_f32_e32 v90, v71, v71
	v_pk_add_f32 v[88:89], v[88:89], v[88:89] op_sel:[0,1] op_sel_hi:[1,0]
	v_mov_b32_e32 v87, v0
	v_mov_b32_e32 v89, v90
	v_mul_f32_e32 v0, v75, v75
	v_mul_f32_e32 v91, v72, v72
	v_pk_add_f32 v[86:87], v[86:87], v[88:89]
	v_pk_fma_f32 v[88:89], v[74:75], v[74:75], v[0:1] op_sel_hi:[1,1,0]
	v_mul_f32_e32 v0, v77, v77
	v_mul_f32_e32 v92, v73, v73
	v_mov_b32_e32 v89, v91
	v_pk_fma_f32 v[90:91], v[76:77], v[76:77], v[0:1] op_sel_hi:[1,1,0]
	s_nop 0
	v_mov_b32_e32 v91, v92
	v_pk_add_f32 v[88:89], v[88:89], v[90:91]
	s_nop 0
	v_pk_add_f32 v[86:87], v[86:87], v[88:89]
	s_nop 0
	v_add_f32_e32 v0, v86, v87
	ds_bpermute_b32 v86, v171, v0
	s_waitcnt lgkmcnt(0)
	v_add_f32_e32 v0, v0, v86
	ds_bpermute_b32 v86, v170, v0
	s_waitcnt lgkmcnt(0)
	v_add_f32_e32 v0, v0, v86
	v_fmamk_f32 v0, v0, 0x3c800000, v220
	v_cmp_gt_f32_e32 vcc, s45, v0
	v_mul_f32_e32 v86, 0x4f800000, v0
	s_nop 0
	v_cndmask_b32_e32 v0, v0, v86, vcc
	v_sqrt_f32_e32 v86, v0
	s_nop 0
	v_add_u32_e32 v87, -1, v86
	v_fma_f32 v88, -v87, v86, v0
	v_cmp_ge_f32_e64 s[6:7], 0, v88
	v_add_u32_e32 v88, 1, v86
	s_nop 0
	v_cndmask_b32_e64 v87, v86, v87, s[6:7]
	v_fma_f32 v86, -v88, v86, v0
	v_cmp_lt_f32_e64 s[6:7], 0, v86
	s_nop 1
	v_cndmask_b32_e64 v86, v87, v88, s[6:7]
	v_mul_f32_e32 v87, 0x37800000, v86
	v_cndmask_b32_e32 v86, v86, v87, vcc
	v_cmp_class_f32_e32 vcc, v0, v221
	s_nop 1
	v_cndmask_b32_e32 v0, v86, v0, vcc
	v_div_scale_f32 v86, s[6:7], v0, v0, 1.0
	v_rcp_f32_e32 v87, v86
	s_nop 0
	v_fma_f32 v88, -v86, v87, 1.0
	v_fmac_f32_e32 v87, v88, v87
	v_div_scale_f32 v88, vcc, 1.0, v0, 1.0
	v_mul_f32_e32 v89, v88, v87
	v_fma_f32 v90, -v86, v89, v88
	v_fmac_f32_e32 v89, v90, v87
	v_fma_f32 v86, -v86, v89, v88
	v_div_fmas_f32 v86, v86, v87, v89
	v_div_fixup_f32 v0, v86, v0, 1.0
	v_pk_mul_f32 v[82:83], v[82:83], v[0:1] op_sel_hi:[1,0]
	v_pk_mul_f32 v[84:85], v[84:85], v[0:1] op_sel_hi:[1,0]
	v_pk_mul_f32 v[78:79], v[78:79], v[0:1] op_sel_hi:[1,0]
	v_pk_mul_f32 v[80:81], v[80:81], v[0:1] op_sel_hi:[1,0]
	v_mad_i64_i32 v[86:87], s[6:7], v174, s44, v[160:161]
	v_pk_mul_f32 v[84:85], v[148:149], v[84:85]
	v_pk_mul_f32 v[82:83], v[150:151], v[82:83]
	v_pk_mul_f32 v[88:89], v[144:145], v[80:81]
	v_pk_mul_f32 v[80:81], v[146:147], v[78:79]
	v_lshl_add_u64 v[86:87], v[86:87], 0, v[162:163]
	v_cvt_pk_bf16_f32 v78, v82, v83
	v_cvt_pk_bf16_f32 v79, v84, v85
	v_cvt_pk_bf16_f32 v80, v80, v81
	v_cvt_pk_bf16_f32 v81, v88, v89
	v_pk_mul_f32 v[74:75], v[74:75], v[0:1] op_sel_hi:[1,0]
	v_pk_mul_f32 v[76:77], v[76:77], v[0:1] op_sel_hi:[1,0]
	v_pk_mul_f32 v[70:71], v[70:71], v[0:1] op_sel_hi:[1,0]
	v_pk_mul_f32 v[72:73], v[72:73], v[0:1] op_sel_hi:[1,0]
	global_store_dwordx4 v[86:87], v[78:81], off nt
	v_pk_mul_f32 v[76:77], v[156:157], v[76:77]
	v_pk_mul_f32 v[74:75], v[158:159], v[74:75]
	v_pk_mul_f32 v[78:79], v[152:153], v[72:73]
	v_pk_mul_f32 v[72:73], v[154:155], v[70:71]
	v_cvt_pk_bf16_f32 v70, v74, v75
	v_cvt_pk_bf16_f32 v71, v76, v77
	v_cvt_pk_bf16_f32 v72, v72, v73
	v_cvt_pk_bf16_f32 v73, v78, v79
	global_store_dwordx4 v[86:87], v[70:73], off offset:64 nt
	v_mul_f32_e32 v0, v54, v54
	s_nop 0
	v_pk_mul_f32 v[70:71], v[68:69], v[68:69]
	v_pk_mul_f32 v[72:73], v[66:67], v[66:67]
	s_nop 0
	v_pk_mov_b32 v[74:75], v[72:73], v[70:71] op_sel:[1,0]
	v_mov_b32_e32 v73, v71
	v_pk_add_f32 v[70:71], v[74:75], v[72:73]
	v_pk_mul_f32 v[72:73], v[64:65], v[64:65]
	v_pk_mul_f32 v[74:75], v[62:63], v[62:63]
	v_pk_add_f32 v[70:71], v[70:71], v[70:71] op_sel:[0,1] op_sel_hi:[1,0]
	v_pk_mov_b32 v[76:77], v[74:75], v[72:73] op_sel:[1,0]
	v_mov_b32_e32 v75, v73
	v_pk_add_f32 v[72:73], v[76:77], v[74:75]
	v_mul_f32_e32 v74, v55, v55
	v_pk_add_f32 v[72:73], v[72:73], v[72:73] op_sel:[0,1] op_sel_hi:[1,0]
	v_mov_b32_e32 v71, v0
	v_mov_b32_e32 v73, v74
	v_mul_f32_e32 v0, v59, v59
	v_mul_f32_e32 v75, v56, v56
	v_pk_add_f32 v[70:71], v[70:71], v[72:73]
	v_pk_fma_f32 v[72:73], v[58:59], v[58:59], v[0:1] op_sel_hi:[1,1,0]
	v_mul_f32_e32 v0, v61, v61
	v_mul_f32_e32 v76, v57, v57
	v_mov_b32_e32 v73, v75
	v_pk_fma_f32 v[74:75], v[60:61], v[60:61], v[0:1] op_sel_hi:[1,1,0]
	s_nop 0
	v_mov_b32_e32 v75, v76
	v_pk_add_f32 v[72:73], v[72:73], v[74:75]
	s_nop 0
	v_pk_add_f32 v[70:71], v[70:71], v[72:73]
	s_nop 0
	v_add_f32_e32 v0, v70, v71
	ds_bpermute_b32 v70, v171, v0
	s_waitcnt lgkmcnt(0)
	v_add_f32_e32 v0, v0, v70
	ds_bpermute_b32 v70, v170, v0
	s_waitcnt lgkmcnt(0)
; #define PG8_GAS __attribute__((address_space(1)))
; __device__ __forceinline__ unsigned cvtpk(float lo, float hi) { f32x2 v = {lo, hi}; bf16x2_t b = __builtin_convertvector(v, bf16x2_t); return __builtin_bit_cast(unsigned, b); }
;     __device__ __forceinline__ void operator()(const f32x4 (&acc)[2][2][4][2], const Unit& u, int wr, int wc, int fr, int fq) const {
;     ...
;                     float ss = 0.f;
; #pragma unroll
;                     for (int bj = 0; bj < 2; ++bj)
; #pragma unroll
;                         for (int n = 0; n < 2; ++n) { const f32x4 x = acc[ai][bj][m][n]; ss += (x[0] * x[0] + x[1] * x[1]) + (x[2] * x[2] + x[3] * x[3]); }
;                     ss += __shfl_xor(ss, 16); ss += __shfl_xor(ss, 32);
;                     const float rstd = 1.0f / sqrtf(ss * (1.0f / 64.0f) + 1e-6f);
;                     bf16_t* p = O + (size_t)(row0 + ai * HALF + m * 16) * 3072 + colh;
; #pragma unroll
;                     for (int bj = 0; bj < 2; ++bj) {
;                         const f32x4 v0 = acc[ai][bj][m][0] * rstd * gv[bj][0], v1 = acc[ai][bj][m][1] * rstd * gv[bj][1];
;                         u32x4 w; w.x = cvtpk(v0[0], v0[1]); w.y = cvtpk(v0[2], v0[3]); w.z = cvtpk(v1[0], v1[1]); w.w = cvtpk(v1[2], v1[3]);
;                         __builtin_nontemporal_store(w, (PG8_GAS u32x4*)(p + 32 * bj));
;                     }
	v_add_f32_e32 v0, v0, v70
	v_fmamk_f32 v0, v0, 0x3c800000, v220
	v_cmp_gt_f32_e32 vcc, s45, v0
	v_mul_f32_e32 v70, 0x4f800000, v0
	s_nop 0
	v_cndmask_b32_e32 v0, v0, v70, vcc
	v_sqrt_f32_e32 v70, v0
	s_nop 0
	v_add_u32_e32 v71, -1, v70
	v_fma_f32 v72, -v71, v70, v0
	v_cmp_ge_f32_e64 s[6:7], 0, v72
	v_add_u32_e32 v72, 1, v70
	s_nop 0
	v_cndmask_b32_e64 v71, v70, v71, s[6:7]
	v_fma_f32 v70, -v72, v70, v0
	v_cmp_lt_f32_e64 s[6:7], 0, v70
	s_nop 1
	v_cndmask_b32_e64 v70, v71, v72, s[6:7]
	v_mul_f32_e32 v71, 0x37800000, v70
	v_cndmask_b32_e32 v70, v70, v71, vcc
	v_cmp_class_f32_e32 vcc, v0, v221
	s_nop 1
	v_cndmask_b32_e32 v0, v70, v0, vcc
	v_div_scale_f32 v70, s[6:7], v0, v0, 1.0
	v_rcp_f32_e32 v71, v70
	s_nop 0
	v_fma_f32 v72, -v70, v71, 1.0
	v_fmac_f32_e32 v71, v72, v71
	v_div_scale_f32 v72, vcc, 1.0, v0, 1.0
	v_mul_f32_e32 v73, v72, v71
	v_fma_f32 v74, -v70, v73, v72
	v_fmac_f32_e32 v73, v74, v71
	v_fma_f32 v70, -v70, v73, v72
	v_div_fmas_f32 v70, v70, v71, v73
	v_div_fixup_f32 v0, v70, v0, 1.0
	v_pk_mul_f32 v[66:67], v[66:67], v[0:1] op_sel_hi:[1,0]
	v_pk_mul_f32 v[68:69], v[68:69], v[0:1] op_sel_hi:[1,0]
	v_pk_mul_f32 v[62:63], v[62:63], v[0:1] op_sel_hi:[1,0]
	v_pk_mul_f32 v[64:65], v[64:65], v[0:1] op_sel_hi:[1,0]
	v_mad_i64_i32 v[70:71], s[6:7], v173, s44, v[160:161]
	v_pk_mul_f32 v[68:69], v[148:149], v[68:69]
	v_pk_mul_f32 v[66:67], v[150:151], v[66:67]
	v_pk_mul_f32 v[72:73], v[144:145], v[64:65]
	v_pk_mul_f32 v[64:65], v[146:147], v[62:63]
	v_lshl_add_u64 v[70:71], v[70:71], 0, v[162:163]
	v_cvt_pk_bf16_f32 v62, v66, v67
	v_cvt_pk_bf16_f32 v63, v68, v69
	v_cvt_pk_bf16_f32 v64, v64, v65
	v_cvt_pk_bf16_f32 v65, v72, v73
	v_pk_mul_f32 v[58:59], v[58:59], v[0:1] op_sel_hi:[1,0]
	v_pk_mul_f32 v[60:61], v[60:61], v[0:1] op_sel_hi:[1,0]
	v_pk_mul_f32 v[54:55], v[54:55], v[0:1] op_sel_hi:[1,0]
	v_pk_mul_f32 v[56:57], v[56:57], v[0:1] op_sel_hi:[1,0]
	global_store_dwordx4 v[70:71], v[62:65], off nt
	v_pk_mul_f32 v[60:61], v[156:157], v[60:61]
	v_pk_mul_f32 v[58:59], v[158:159], v[58:59]
	v_pk_mul_f32 v[62:63], v[152:153], v[56:57]
	v_pk_mul_f32 v[56:57], v[154:155], v[54:55]
	v_cvt_pk_bf16_f32 v54, v58, v59
	v_cvt_pk_bf16_f32 v55, v60, v61
	v_cvt_pk_bf16_f32 v56, v56, v57
	v_cvt_pk_bf16_f32 v57, v62, v63
	global_store_dwordx4 v[70:71], v[54:57], off offset:64 nt
	v_mul_f32_e32 v0, v38, v38
	s_nop 0
	v_pk_mul_f32 v[54:55], v[52:53], v[52:53]
	v_pk_mul_f32 v[56:57], v[50:51], v[50:51]
	s_nop 0
	v_pk_mov_b32 v[58:59], v[56:57], v[54:55] op_sel:[1,0]
	v_mov_b32_e32 v57, v55
	v_pk_add_f32 v[54:55], v[58:59], v[56:57]
	v_pk_mul_f32 v[56:57], v[48:49], v[48:49]
	v_pk_mul_f32 v[58:59], v[46:47], v[46:47]
	v_pk_add_f32 v[54:55], v[54:55], v[54:55] op_sel:[0,1] op_sel_hi:[1,0]
	v_pk_mov_b32 v[60:61], v[58:59], v[56:57] op_sel:[1,0]
	v_mov_b32_e32 v59, v57
	v_pk_add_f32 v[56:57], v[60:61], v[58:59]
	v_mul_f32_e32 v58, v39, v39
	v_pk_add_f32 v[56:57], v[56:57], v[56:57] op_sel:[0,1] op_sel_hi:[1,0]
	v_mov_b32_e32 v55, v0
	v_mov_b32_e32 v57, v58
	v_mul_f32_e32 v0, v43, v43
	v_mul_f32_e32 v59, v40, v40
	v_pk_add_f32 v[54:55], v[54:55], v[56:57]
	v_pk_fma_f32 v[56:57], v[42:43], v[42:43], v[0:1] op_sel_hi:[1,1,0]
	v_mul_f32_e32 v0, v45, v45
	v_mul_f32_e32 v60, v41, v41
	v_mov_b32_e32 v57, v59
	v_pk_fma_f32 v[58:59], v[44:45], v[44:45], v[0:1] op_sel_hi:[1,1,0]
	s_nop 0
	v_mov_b32_e32 v59, v60
	v_pk_add_f32 v[56:57], v[56:57], v[58:59]
	s_nop 0
	v_pk_add_f32 v[54:55], v[54:55], v[56:57]
	s_nop 0
	v_add_f32_e32 v0, v54, v55
	ds_bpermute_b32 v54, v171, v0
	s_waitcnt lgkmcnt(0)
	v_add_f32_e32 v0, v0, v54
	ds_bpermute_b32 v54, v170, v0
	s_waitcnt lgkmcnt(0)
	v_add_f32_e32 v0, v0, v54
	v_fmamk_f32 v0, v0, 0x3c800000, v220
	v_cmp_gt_f32_e32 vcc, s45, v0
	v_mul_f32_e32 v54, 0x4f800000, v0
	s_nop 0
	v_cndmask_b32_e32 v0, v0, v54, vcc
	v_sqrt_f32_e32 v54, v0
	s_nop 0
	v_add_u32_e32 v55, -1, v54
	v_fma_f32 v56, -v55, v54, v0
	v_cmp_ge_f32_e64 s[6:7], 0, v56
	v_add_u32_e32 v56, 1, v54
	s_nop 0
	v_cndmask_b32_e64 v55, v54, v55, s[6:7]
	v_fma_f32 v54, -v56, v54, v0
	v_cmp_lt_f32_e64 s[6:7], 0, v54
	s_nop 1
	v_cndmask_b32_e64 v54, v55, v56, s[6:7]
	v_mul_f32_e32 v55, 0x37800000, v54
	v_cndmask_b32_e32 v54, v54, v55, vcc
	v_cmp_class_f32_e32 vcc, v0, v221
	s_nop 1
	v_cndmask_b32_e32 v0, v54, v0, vcc
	v_div_scale_f32 v54, s[6:7], v0, v0, 1.0
	v_rcp_f32_e32 v55, v54
	s_nop 0
	v_fma_f32 v56, -v54, v55, 1.0
	v_fmac_f32_e32 v55, v56, v55
	v_div_scale_f32 v56, vcc, 1.0, v0, 1.0
	v_mul_f32_e32 v57, v56, v55
	v_fma_f32 v58, -v54, v57, v56
	v_fmac_f32_e32 v57, v58, v55
	v_fma_f32 v54, -v54, v57, v56
	v_div_fmas_f32 v54, v54, v55, v57
	v_div_fixup_f32 v0, v54, v0, 1.0
	v_pk_mul_f32 v[50:51], v[50:51], v[0:1] op_sel_hi:[1,0]
	v_pk_mul_f32 v[52:53], v[52:53], v[0:1] op_sel_hi:[1,0]
	v_pk_mul_f32 v[46:47], v[46:47], v[0:1] op_sel_hi:[1,0]
	v_pk_mul_f32 v[48:49], v[48:49], v[0:1] op_sel_hi:[1,0]
	v_mad_i64_i32 v[54:55], s[6:7], v172, s44, v[160:161]
	v_pk_mul_f32 v[52:53], v[148:149], v[52:53]
	v_pk_mul_f32 v[50:51], v[150:151], v[50:51]
	v_pk_mul_f32 v[56:57], v[144:145], v[48:49]
	v_pk_mul_f32 v[48:49], v[146:147], v[46:47]
	v_lshl_add_u64 v[54:55], v[54:55], 0, v[162:163]
	v_cvt_pk_bf16_f32 v46, v50, v51
	v_cvt_pk_bf16_f32 v47, v52, v53
	v_cvt_pk_bf16_f32 v48, v48, v49
	v_cvt_pk_bf16_f32 v49, v56, v57
	v_pk_mul_f32 v[42:43], v[42:43], v[0:1] op_sel_hi:[1,0]
	v_pk_mul_f32 v[44:45], v[44:45], v[0:1] op_sel_hi:[1,0]
	v_pk_mul_f32 v[38:39], v[38:39], v[0:1] op_sel_hi:[1,0]
	v_pk_mul_f32 v[40:41], v[40:41], v[0:1] op_sel_hi:[1,0]
	global_store_dwordx4 v[54:55], v[46:49], off nt
	v_pk_mul_f32 v[44:45], v[156:157], v[44:45]
	v_pk_mul_f32 v[42:43], v[158:159], v[42:43]
; #define PG8_GAS __attribute__((address_space(1)))
; __device__ __forceinline__ unsigned cvtpk(float lo, float hi) { f32x2 v = {lo, hi}; bf16x2_t b = __builtin_convertvector(v, bf16x2_t); return __builtin_bit_cast(unsigned, b); }
;     __device__ __forceinline__ void operator()(const f32x4 (&acc)[2][2][4][2], const Unit& u, int wr, int wc, int fr, int fq) const {
;     ...
;                     float ss = 0.f;
; #pragma unroll
;                     for (int bj = 0; bj < 2; ++bj)
; #pragma unroll
;                         for (int n = 0; n < 2; ++n) { const f32x4 x = acc[ai][bj][m][n]; ss += (x[0] * x[0] + x[1] * x[1]) + (x[2] * x[2] + x[3] * x[3]); }
;                     ss += __shfl_xor(ss, 16); ss += __shfl_xor(ss, 32);
;                     const float rstd = 1.0f / sqrtf(ss * (1.0f / 64.0f) + 1e-6f);
;                     bf16_t* p = O + (size_t)(row0 + ai * HALF + m * 16) * 3072 + colh;
; #pragma unroll
;                     for (int bj = 0; bj < 2; ++bj) {
;                         const f32x4 v0 = acc[ai][bj][m][0] * rstd * gv[bj][0], v1 = acc[ai][bj][m][1] * rstd * gv[bj][1];
;                         u32x4 w; w.x = cvtpk(v0[0], v0[1]); w.y = cvtpk(v0[2], v0[3]); w.z = cvtpk(v1[0], v1[1]); w.w = cvtpk(v1[2], v1[3]);
;                         __builtin_nontemporal_store(w, (PG8_GAS u32x4*)(p + 32 * bj));
;                     }
	v_pk_mul_f32 v[46:47], v[152:153], v[40:41]
	v_pk_mul_f32 v[40:41], v[154:155], v[38:39]
	v_cvt_pk_bf16_f32 v38, v42, v43
	v_cvt_pk_bf16_f32 v39, v44, v45
	v_cvt_pk_bf16_f32 v40, v40, v41
	v_cvt_pk_bf16_f32 v41, v46, v47
	global_store_dwordx4 v[54:55], v[38:41], off offset:64 nt
	v_mul_f32_e32 v0, v22, v22
	s_nop 0
	v_pk_mul_f32 v[38:39], v[36:37], v[36:37]
	v_pk_mul_f32 v[40:41], v[34:35], v[34:35]
	s_nop 0
	v_pk_mov_b32 v[42:43], v[40:41], v[38:39] op_sel:[1,0]
	v_mov_b32_e32 v41, v39
	v_pk_add_f32 v[38:39], v[42:43], v[40:41]
	v_pk_mul_f32 v[40:41], v[32:33], v[32:33]
	v_pk_mul_f32 v[42:43], v[30:31], v[30:31]
	v_pk_add_f32 v[38:39], v[38:39], v[38:39] op_sel:[0,1] op_sel_hi:[1,0]
	v_pk_mov_b32 v[44:45], v[42:43], v[40:41] op_sel:[1,0]
	v_mov_b32_e32 v43, v41
	v_pk_add_f32 v[40:41], v[44:45], v[42:43]
	v_mul_f32_e32 v42, v23, v23
	v_pk_add_f32 v[40:41], v[40:41], v[40:41] op_sel:[0,1] op_sel_hi:[1,0]
	v_mov_b32_e32 v39, v0
	v_mov_b32_e32 v41, v42
	v_mul_f32_e32 v0, v27, v27
	v_mul_f32_e32 v43, v24, v24
	v_pk_add_f32 v[38:39], v[38:39], v[40:41]
	v_pk_fma_f32 v[40:41], v[26:27], v[26:27], v[0:1] op_sel_hi:[1,1,0]
	v_mul_f32_e32 v0, v29, v29
	v_mul_f32_e32 v44, v25, v25
	v_mov_b32_e32 v41, v43
	v_pk_fma_f32 v[42:43], v[28:29], v[28:29], v[0:1] op_sel_hi:[1,1,0]
	s_nop 0
	v_mov_b32_e32 v43, v44
	v_pk_add_f32 v[40:41], v[40:41], v[42:43]
	s_nop 0
	v_pk_add_f32 v[38:39], v[38:39], v[40:41]
	s_nop 0
	v_add_f32_e32 v0, v38, v39
	ds_bpermute_b32 v38, v171, v0
	s_waitcnt lgkmcnt(0)
	v_add_f32_e32 v0, v0, v38
	ds_bpermute_b32 v38, v170, v0
	s_waitcnt lgkmcnt(0)
	v_add_f32_e32 v0, v0, v38
	v_fmamk_f32 v0, v0, 0x3c800000, v220
	v_cmp_gt_f32_e32 vcc, s45, v0
	v_mul_f32_e32 v38, 0x4f800000, v0
	s_nop 0
	v_cndmask_b32_e32 v0, v0, v38, vcc
	v_sqrt_f32_e32 v38, v0
	s_nop 0
	v_add_u32_e32 v39, -1, v38
	v_fma_f32 v40, -v39, v38, v0
	v_cmp_ge_f32_e64 s[6:7], 0, v40
	v_add_u32_e32 v40, 1, v38
	s_nop 0
	v_cndmask_b32_e64 v39, v38, v39, s[6:7]
	v_fma_f32 v38, -v40, v38, v0
	v_cmp_lt_f32_e64 s[6:7], 0, v38
	s_nop 1
	v_cndmask_b32_e64 v38, v39, v40, s[6:7]
	v_mul_f32_e32 v39, 0x37800000, v38
	v_cndmask_b32_e32 v38, v38, v39, vcc
	v_cmp_class_f32_e32 vcc, v0, v221
	s_nop 1
	v_cndmask_b32_e32 v0, v38, v0, vcc
	v_div_scale_f32 v38, s[6:7], v0, v0, 1.0
	v_rcp_f32_e32 v39, v38
	s_nop 0
	v_fma_f32 v40, -v38, v39, 1.0
	v_fmac_f32_e32 v39, v40, v39
	v_div_scale_f32 v40, vcc, 1.0, v0, 1.0
	v_mul_f32_e32 v41, v40, v39
	v_fma_f32 v42, -v38, v41, v40
	v_fmac_f32_e32 v41, v42, v39
	v_fma_f32 v38, -v38, v41, v40
	v_div_fmas_f32 v38, v38, v39, v41
	v_div_fixup_f32 v0, v38, v0, 1.0
	v_pk_mul_f32 v[34:35], v[34:35], v[0:1] op_sel_hi:[1,0]
	v_pk_mul_f32 v[36:37], v[36:37], v[0:1] op_sel_hi:[1,0]
	v_pk_mul_f32 v[30:31], v[30:31], v[0:1] op_sel_hi:[1,0]
	v_pk_mul_f32 v[32:33], v[32:33], v[0:1] op_sel_hi:[1,0]
	v_mad_i64_i32 v[38:39], s[6:7], v169, s44, v[160:161]
	v_pk_mul_f32 v[36:37], v[148:149], v[36:37]
	v_pk_mul_f32 v[34:35], v[150:151], v[34:35]
	v_pk_mul_f32 v[40:41], v[144:145], v[32:33]
	v_pk_mul_f32 v[32:33], v[146:147], v[30:31]
	v_lshl_add_u64 v[38:39], v[38:39], 0, v[162:163]
	v_cvt_pk_bf16_f32 v30, v34, v35
	v_cvt_pk_bf16_f32 v31, v36, v37
	v_cvt_pk_bf16_f32 v32, v32, v33
	v_cvt_pk_bf16_f32 v33, v40, v41
	v_pk_mul_f32 v[26:27], v[26:27], v[0:1] op_sel_hi:[1,0]
	v_pk_mul_f32 v[28:29], v[28:29], v[0:1] op_sel_hi:[1,0]
	v_pk_mul_f32 v[22:23], v[22:23], v[0:1] op_sel_hi:[1,0]
	v_pk_mul_f32 v[24:25], v[24:25], v[0:1] op_sel_hi:[1,0]
	global_store_dwordx4 v[38:39], v[30:33], off nt
	v_pk_mul_f32 v[28:29], v[156:157], v[28:29]
	v_pk_mul_f32 v[26:27], v[158:159], v[26:27]
	v_pk_mul_f32 v[30:31], v[152:153], v[24:25]
	v_pk_mul_f32 v[24:25], v[154:155], v[22:23]
	v_cvt_pk_bf16_f32 v22, v26, v27
	v_cvt_pk_bf16_f32 v23, v28, v29
	v_cvt_pk_bf16_f32 v24, v24, v25
	v_cvt_pk_bf16_f32 v25, v30, v31
	global_store_dwordx4 v[38:39], v[22:25], off offset:64 nt
	v_mul_f32_e32 v0, v6, v6
	s_nop 0
	v_pk_mul_f32 v[22:23], v[20:21], v[20:21]
	v_pk_mul_f32 v[24:25], v[18:19], v[18:19]
	s_nop 0
	v_pk_mov_b32 v[26:27], v[24:25], v[22:23] op_sel:[1,0]
	v_mov_b32_e32 v25, v23
	v_pk_add_f32 v[22:23], v[26:27], v[24:25]
	v_pk_mul_f32 v[24:25], v[16:17], v[16:17]
	v_pk_mul_f32 v[26:27], v[14:15], v[14:15]
	v_pk_add_f32 v[22:23], v[22:23], v[22:23] op_sel:[0,1] op_sel_hi:[1,0]
	v_pk_mov_b32 v[28:29], v[26:27], v[24:25] op_sel:[1,0]
	v_mov_b32_e32 v27, v25
	v_pk_add_f32 v[24:25], v[28:29], v[26:27]
	v_mul_f32_e32 v26, v7, v7
	v_pk_add_f32 v[24:25], v[24:25], v[24:25] op_sel:[0,1] op_sel_hi:[1,0]
	v_mov_b32_e32 v23, v0
	v_mov_b32_e32 v25, v26
	v_mul_f32_e32 v0, v11, v11
	v_mul_f32_e32 v27, v8, v8
	v_pk_add_f32 v[22:23], v[22:23], v[24:25]
	v_pk_fma_f32 v[24:25], v[10:11], v[10:11], v[0:1] op_sel_hi:[1,1,0]
	v_mul_f32_e32 v0, v13, v13
	v_mul_f32_e32 v28, v9, v9
	v_mov_b32_e32 v25, v27
	v_pk_fma_f32 v[26:27], v[12:13], v[12:13], v[0:1] op_sel_hi:[1,1,0]
	s_nop 0
	v_mov_b32_e32 v27, v28
	v_pk_add_f32 v[24:25], v[24:25], v[26:27]
	s_nop 0
	v_pk_add_f32 v[22:23], v[22:23], v[24:25]
	s_nop 0
	v_add_f32_e32 v0, v22, v23
	ds_bpermute_b32 v22, v171, v0
	s_waitcnt lgkmcnt(0)
; #define PG8_GAS __attribute__((address_space(1)))
; __device__ __forceinline__ unsigned cvtpk(float lo, float hi) { f32x2 v = {lo, hi}; bf16x2_t b = __builtin_convertvector(v, bf16x2_t); return __builtin_bit_cast(unsigned, b); }
;     __device__ __forceinline__ void operator()(const f32x4 (&acc)[2][2][4][2], const Unit& u, int wr, int wc, int fr, int fq) const {
;     ...
;                     ss += __shfl_xor(ss, 16); ss += __shfl_xor(ss, 32);
;                     const float rstd = 1.0f / sqrtf(ss * (1.0f / 64.0f) + 1e-6f);
;                     bf16_t* p = O + (size_t)(row0 + ai * HALF + m * 16) * 3072 + colh;
; #pragma unroll
;                     for (int bj = 0; bj < 2; ++bj) {
;                         const f32x4 v0 = acc[ai][bj][m][0] * rstd * gv[bj][0], v1 = acc[ai][bj][m][1] * rstd * gv[bj][1];
;                         u32x4 w; w.x = cvtpk(v0[0], v0[1]); w.y = cvtpk(v0[2], v0[3]); w.z = cvtpk(v1[0], v1[1]); w.w = cvtpk(v1[2], v1[3]);
;                         __builtin_nontemporal_store(w, (PG8_GAS u32x4*)(p + 32 * bj));
	v_add_f32_e32 v0, v0, v22
	ds_bpermute_b32 v22, v170, v0
	s_waitcnt lgkmcnt(0)
	v_add_f32_e32 v0, v0, v22
	v_fmamk_f32 v0, v0, 0x3c800000, v220
	v_cmp_gt_f32_e32 vcc, s45, v0
	v_mul_f32_e32 v22, 0x4f800000, v0
	s_nop 0
	v_cndmask_b32_e32 v0, v0, v22, vcc
	v_sqrt_f32_e32 v22, v0
	s_nop 0
	v_add_u32_e32 v23, -1, v22
	v_fma_f32 v24, -v23, v22, v0
	v_cmp_ge_f32_e64 s[6:7], 0, v24
	v_add_u32_e32 v24, 1, v22
	s_nop 0
	v_cndmask_b32_e64 v23, v22, v23, s[6:7]
	v_fma_f32 v22, -v24, v22, v0
	v_cmp_lt_f32_e64 s[6:7], 0, v22
	s_nop 1
	v_cndmask_b32_e64 v22, v23, v24, s[6:7]
	v_mul_f32_e32 v23, 0x37800000, v22
	v_cndmask_b32_e32 v22, v22, v23, vcc
	v_cmp_class_f32_e32 vcc, v0, v221
	s_nop 1
	v_cndmask_b32_e32 v0, v22, v0, vcc
	v_div_scale_f32 v22, s[6:7], v0, v0, 1.0
	v_rcp_f32_e32 v23, v22
	s_nop 0
	v_fma_f32 v24, -v22, v23, 1.0
	v_fmac_f32_e32 v23, v24, v23
	v_div_scale_f32 v24, vcc, 1.0, v0, 1.0
	v_mul_f32_e32 v25, v24, v23
	v_fma_f32 v26, -v22, v25, v24
	v_fmac_f32_e32 v25, v26, v23
	v_fma_f32 v22, -v22, v25, v24
	v_div_fmas_f32 v22, v22, v23, v25
	v_div_fixup_f32 v0, v22, v0, 1.0
	v_mad_i64_i32 v[22:23], s[6:7], v168, s44, v[160:161]
	v_pk_mul_f32 v[18:19], v[18:19], v[0:1] op_sel_hi:[1,0]
	v_pk_mul_f32 v[20:21], v[20:21], v[0:1] op_sel_hi:[1,0]
	v_pk_mul_f32 v[14:15], v[14:15], v[0:1] op_sel_hi:[1,0]
	v_pk_mul_f32 v[16:17], v[16:17], v[0:1] op_sel_hi:[1,0]
	v_lshl_add_u64 v[160:161], v[22:23], 0, v[162:163]
	v_pk_mul_f32 v[20:21], v[148:149], v[20:21]
	v_pk_mul_f32 v[18:19], v[150:151], v[18:19]
	v_pk_mul_f32 v[22:23], v[144:145], v[16:17]
	v_pk_mul_f32 v[16:17], v[146:147], v[14:15]
	v_pk_mul_f32 v[10:11], v[10:11], v[0:1] op_sel_hi:[1,0]
	v_pk_mul_f32 v[12:13], v[12:13], v[0:1] op_sel_hi:[1,0]
	v_pk_mul_f32 v[6:7], v[6:7], v[0:1] op_sel_hi:[1,0]
	v_pk_mul_f32 v[8:9], v[8:9], v[0:1] op_sel_hi:[1,0]
	v_cvt_pk_bf16_f32 v14, v18, v19
	v_cvt_pk_bf16_f32 v15, v20, v21
	v_cvt_pk_bf16_f32 v16, v16, v17
	v_cvt_pk_bf16_f32 v17, v22, v23
	v_pk_mul_f32 v[12:13], v[156:157], v[12:13]
	v_pk_mul_f32 v[10:11], v[158:159], v[10:11]
	v_pk_mul_f32 v[8:9], v[152:153], v[8:9]
	v_pk_mul_f32 v[6:7], v[154:155], v[6:7]
	global_store_dwordx4 v[160:161], v[14:17], off nt
